# stack6 + XCC-local barrier as fire-and-forget arrival + polling the arrival counter
# baseline (speedup 1.0000x reference)
_Z4mega6Paramsii:
	s_load_dwordx4 s[56:59], s[0:1], 0xa0
	s_load_dwordx2 s[34:35], s[0:1], 0xb0
	v_writelane_b32 v251, s2, 0
	s_add_u32 s2, s0, 0xb0
	s_addc_u32 s3, s1, 0
	v_writelane_b32 v251, s2, 1
	s_waitcnt lgkmcnt(0)
	s_mov_b32 s101, 0
	s_add_u32 s12, s56, 0x6180000
	s_addc_u32 s13, s57, 0
	v_writelane_b32 v251, s3, 2
	s_sub_i32 s2, s59, s58
	s_cmp_lt_i32 s2, 2
	s_cbranch_scc1 .LBB0_5
	v_readlane_b32 s3, v251, 0
	s_mov_b32 s2, 0
	s_cmp_lg_u32 s3, 0
	v_and_b32_e32 v2, 0x3ff, v0
	s_cbranch_scc0 .LBB0_560
	v_cmp_gt_u32_e32 vcc, 4, v2
	s_and_saveexec_b64 s[2:3], vcc

.LBB0_86:
	s_and_b64 vcc, exec, s[2:3]
	s_cbranch_vccz .LBB0_98
	s_waitcnt vmcnt(0)
	s_barrier
	s_mov_b64 s[0:1], exec
	v_readlane_b32 s2, v249, 48
	v_readlane_b32 s3, v249, 49
	s_and_b64 s[2:3], s[0:1], s[2:3]
	s_mov_b64 exec, s[2:3]
	s_cbranch_execz .LBB0_558
	v_readlane_b32 s2, v249, 38
	v_readlane_b32 s4, v251, 3
	v_readlane_b32 s5, v251, 4
	v_mov_b32_e32 v0, s2
	v_readlane_b32 s2, v249, 47
	s_lshl_b32 s80, s2, 6
	s_lshl_b64 s[2:3], s[80:81], 2
	s_add_u32 s2, s4, s2
	s_addc_u32 s3, s5, s3
	s_waitcnt vmcnt(0) expcnt(0) lgkmcnt(0)
	ds_read_b32 v2, v0
	global_atomic_add v154, v152, s[2:3] offset:1536
	s_add_i32 s101, s101, 1
	s_waitcnt lgkmcnt(0)
	v_readfirstlane_b32 s4, v2
	s_mov_b32 s5, 0
	s_mul_i32 s4, s4, s101
.Llbar_poll:
	global_load_dword v3, v154, s[2:3] offset:1536 sc1
	s_waitcnt vmcnt(0)
	v_readfirstlane_b32 s6, v3
	s_cmp_ge_u32 s6, s4
	s_cbranch_scc1 .Llbar_join
	s_sleep 1
	s_add_i32 s5, s5, 1
	s_cmp_lt_u32 s5, 0x400000
	s_cbranch_scc1 .Llbar_poll
	s_branch .Llbar_join

.Llbar_join:
	s_waitcnt vmcnt(0)
	buffer_inv sc1
	s_waitcnt vmcnt(0)
